# m34 + level-1 radix scan: the crossing group's bin count per in-lane step is picked with three nested selects on the raw group flags instead of four masked selects and two ORs (31 VALU fewer per row)
# speedup vs baseline: 1.0006x; 1.0006x over previous
.LBB0_1394:
	s_andn2_b64 vcc, exec, s[8:9]
	s_cbranch_vccnz .LBB0_1389
	s_lshl_b32 s8, s11, 13
	s_lshl_b32 s11, s11, 2
	v_add_u32_e32 v3, s11, v2
	v_and_b32_e32 v4, 0x7fc, v3
	v_lshrrev_b32_e32 v6, 3, v3
	v_bitop3_b32 v4, v6, v4, 28 bitop3:0x6c
	v_add_u32_e32 v6, 4, v3
	v_and_b32_e32 v7, 0x7fc, v6
	v_lshrrev_b32_e32 v6, 3, v6
	s_add_i32 s8, s8, 0
	v_bitop3_b32 v6, v6, v7, 28 bitop3:0x6c
	v_lshl_add_u32 v4, v4, 2, s8
	v_lshl_add_u32 v10, v6, 2, s8
	ds_read_b128 v[6:9], v4
	ds_read_b128 v[10:13], v10
	v_add_u32_e32 v4, 8, v3
	v_and_b32_e32 v14, 0x7fc, v4
	v_lshrrev_b32_e32 v4, 3, v4
	v_bitop3_b32 v4, v4, v14, 28 bitop3:0x6c
	v_add_u32_e32 v14, 12, v3
	v_and_b32_e32 v15, 0x7fc, v14
	v_lshrrev_b32_e32 v14, 3, v14
	v_bitop3_b32 v14, v14, v15, 28 bitop3:0x6c
	v_lshl_add_u32 v4, v4, 2, s8
	v_lshl_add_u32 v18, v14, 2, s8
	ds_read_b128 v[14:17], v4
	ds_read_b128 v[18:21], v18
	v_add_u32_e32 v4, 16, v3
	v_and_b32_e32 v22, 0x7fc, v4
	v_lshrrev_b32_e32 v4, 3, v4
	v_bitop3_b32 v4, v4, v22, 28 bitop3:0x6c
	v_add_u32_e32 v22, 20, v3
	v_and_b32_e32 v23, 0x7fc, v22
	v_lshrrev_b32_e32 v22, 3, v22
	v_bitop3_b32 v22, v22, v23, 28 bitop3:0x6c
	v_lshl_add_u32 v4, v4, 2, s8
	v_lshl_add_u32 v26, v22, 2, s8
	ds_read_b128 v[22:25], v4
	ds_read_b128 v[26:29], v26
	v_add_u32_e32 v4, 24, v3
	v_and_b32_e32 v30, 0x7fc, v4
	v_lshrrev_b32_e32 v4, 3, v4
	v_add_u32_e32 v3, 28, v3
	v_bitop3_b32 v4, v4, v30, 28 bitop3:0x6c
	v_and_b32_e32 v30, 0x7fc, v3
	v_lshrrev_b32_e32 v3, 3, v3
	v_lshl_add_u32 v4, v4, 2, s8
	v_bitop3_b32 v3, v3, v30, 28 bitop3:0x6c
	v_lshl_add_u32 v3, v3, 2, s8
	ds_read_b128 v[30:33], v4
	ds_read_b128 v[174:177], v3
	s_waitcnt lgkmcnt(0)
	v_add_u32_e32 v4, v15, v14
	v_add3_u32 v3, v7, v6, v8
	v_add3_u32 v4, v4, v16, v17
	v_add_u32_e32 v34, v23, v22
	v_add_u32_e32 v35, v31, v30
	v_add3_u32 v3, v3, v9, v10
	v_add3_u32 v4, v4, v18, v19
	v_add3_u32 v34, v34, v24, v25
	v_add3_u32 v35, v35, v32, v33
	v_add3_u32 v3, v3, v11, v12
	v_add3_u32 v4, v4, v20, v21
	v_add3_u32 v34, v34, v26, v27
	v_add3_u32 v35, v35, v174, v175
	v_add3_u32 v34, v34, v28, v29
	v_add3_u32 v35, v35, v176, v177
	v_add3_u32 v3, v3, v13, v4
	v_add3_u32 v3, v3, v34, v35
	s_nop 1
	v_add_u32_dpp v173, v3, v3 row_shr:1 row_mask:0xf bank_mask:0xf bound_ctrl:1
	s_nop 1
	v_add_u32_dpp v173, v173, v173 row_shr:2 row_mask:0xf bank_mask:0xf bound_ctrl:1
	s_nop 1
	v_add_u32_dpp v173, v173, v173 row_shr:4 row_mask:0xf bank_mask:0xf bound_ctrl:1
	s_nop 1
	v_add_u32_dpp v173, v173, v173 row_shr:8 row_mask:0xf bank_mask:0xf bound_ctrl:1
	s_nop 1
	v_add_u32_dpp v173, v173, v173 row_bcast:15 row_mask:0xa bank_mask:0xf
	s_nop 1
	v_add_u32_dpp v173, v173, v173 row_bcast:31 row_mask:0xc bank_mask:0xf
	v_sub_u32_e32 v3, v173, v3
	v_add_u32_e32 v35, v3, v35
	v_add_u32_e32 v34, v35, v34
	v_add_u32_e32 v4, v34, v4
	v_cmp_lt_u32_e32 vcc, s87, v173
	v_cmp_gt_u32_e64 s[42:43], s86, v4
	v_cmp_lt_u32_e64 s[44:45], s87, v34
	v_cmp_lt_u32_e64 s[46:47], s87, v35
	s_ff1_i32_b64 s14, vcc
	v_cndmask_b32_e64 v4, v34, v4, s[42:43]
	v_cndmask_b32_e64 v4, v4, v35, s[44:45]
	v_cndmask_b32_e64 v3, v4, v3, s[46:47]
	v_cndmask_b32_e64 v4, v21, v13, s[42:43]
	v_cndmask_b32_e64 v4, v4, v29, s[44:45]
	v_cndmask_b32_e64 v4, v4, v177, s[46:47]
	v_add_u32_e32 v4, v4, v3
	v_cmp_gt_u32_e64 s[50:51], s86, v4
	v_cndmask_b32_e64 v12, v20, v12, s[42:43]
	v_cndmask_b32_e64 v12, v12, v28, s[44:45]
	v_cndmask_b32_e64 v12, v12, v176, s[46:47]
	v_cndmask_b32_e64 v3, v3, v4, s[50:51]
	v_add_u32_e32 v4, v4, v12
	v_cmp_gt_u32_e64 s[52:53], s86, v4
	v_cndmask_b32_e64 v11, v19, v11, s[42:43]
	v_cndmask_b32_e64 v11, v11, v27, s[44:45]
	v_cndmask_b32_e64 v11, v11, v175, s[46:47]
	v_cndmask_b32_e64 v3, v3, v4, s[52:53]
	v_add_u32_e32 v4, v4, v11
	v_cmp_gt_u32_e64 s[56:57], s86, v4
	v_cndmask_b32_e64 v10, v18, v10, s[42:43]
	v_cndmask_b32_e64 v10, v10, v26, s[44:45]
	v_cndmask_b32_e64 v10, v10, v174, s[46:47]
	v_cndmask_b32_e64 v3, v3, v4, s[56:57]
	v_add_u32_e32 v4, v4, v10
	v_cmp_gt_u32_e64 s[58:59], s86, v4
	v_cndmask_b32_e64 v9, v17, v9, s[42:43]
	v_cndmask_b32_e64 v9, v9, v25, s[44:45]
	v_cndmask_b32_e64 v9, v9, v33, s[46:47]
	v_cndmask_b32_e64 v3, v3, v4, s[58:59]
	v_add_u32_e32 v4, v4, v9
	v_cmp_gt_u32_e64 s[60:61], s86, v4
	v_cndmask_b32_e64 v8, v16, v8, s[42:43]
	v_cndmask_b32_e64 v8, v8, v24, s[44:45]
	v_cndmask_b32_e64 v8, v8, v32, s[46:47]
	v_cndmask_b32_e64 v3, v3, v4, s[60:61]
	v_add_u32_e32 v4, v4, v8
	v_cmp_gt_u32_e64 s[62:63], s86, v4
	v_cndmask_b32_e64 v7, v15, v7, s[42:43]
	v_cndmask_b32_e64 v7, v7, v23, s[44:45]
	v_cndmask_b32_e64 v7, v7, v31, s[46:47]
	v_cndmask_b32_e64 v3, v3, v4, s[62:63]
	v_add_u32_e32 v4, v4, v7
	v_cmp_gt_u32_e64 s[64:65], s86, v4
	v_cndmask_b32_e64 v6, v14, v6, s[42:43]
	v_cndmask_b32_e64 v6, v6, v22, s[44:45]
	v_cndmask_b32_e64 v6, v6, v30, s[46:47]
	v_cndmask_b32_e64 v3, v3, v4, s[64:65]
	v_add_u32_e32 v4, v4, v6
	v_cmp_gt_u32_e32 vcc, s86, v4
	s_nop 1
	v_cndmask_b32_e32 v3, v3, v4, vcc
	v_cndmask_b32_e64 v4, 8, 0, s[42:43]
	v_cndmask_b32_e64 v4, v4, 16, s[44:45]
	v_cndmask_b32_e64 v4, v4, 24, s[46:47]
	v_or_b32_e32 v4, v4, v2
	v_subbrev_co_u32_e64 v4, s[42:43], 0, v4, s[50:51]
	v_subbrev_co_u32_e64 v4, s[42:43], 0, v4, s[52:53]
	v_subbrev_co_u32_e64 v4, s[42:43], 0, v4, s[56:57]
	v_subbrev_co_u32_e64 v4, s[42:43], 0, v4, s[58:59]
	v_subbrev_co_u32_e64 v4, s[42:43], 0, v4, s[60:61]
	v_subbrev_co_u32_e64 v4, s[42:43], 0, v4, s[62:63]
	v_subbrev_co_u32_e64 v4, s[42:43], 0, v4, s[64:65]
	v_subbrev_co_u32_e32 v4, vcc, 0, v4, vcc
	s_nop 0
	v_readlane_b32 s12, v4, s14
	v_readlane_b32 s13, v3, s14
	s_and_saveexec_b64 s[8:9], s[40:41]
	s_cbranch_execz .LBB0_1388
	s_lshl_b32 s11, s11, 2
	s_add_i32 s11, s11, 0
	s_sub_i32 s13, 0x100, s13
	s_add_i32 s12, s12, 7
	s_add_i32 s11, s11, 0x22000
	v_mov_b32_e32 v184, s12
	v_mov_b32_e32 v185, s13
	v_mov_b32_e32 v3, s11
	ds_write_b96 v3, v[184:186]
	s_branch .LBB0_1388
